# attention unit prologue: key-bias copy issues both chunks' loads before the single wait (was load-wait-write per chunk)
# baseline (speedup 1.0000x reference)
.LBB0_354:
	s_or_b64 exec, exec, s[6:7]
	v_cndmask_b32_e64 v0, 0, 1, s[52:53]
	v_cmp_ne_u32_e32 vcc, 0, v0
	s_not_b64 s[6:7], vcc
	s_ff1_i32_b64 s6, s[6:7]
	s_min_u32 s6, s6, 64
	s_and_b32 s6, s6, 0x7e
	s_min_u32 s54, s6, s54
	s_ashr_i32 s55, s54, 31
	s_ashr_i32 s62, s56, 6
	s_lshl_b64 s[6:7], s[54:55], 16
	s_lshl_b64 s[52:53], s[10:11], 22
	s_add_u32 s6, s6, s52
	s_addc_u32 s7, s7, s53
	s_lshl_b64 s[6:7], s[6:7], 1
	s_add_u32 s52, s71, s6
	s_addc_u32 s53, s72, s7
	s_lshl_b32 s55, s58, 7
	s_add_u32 s52, s52, s55
	s_addc_u32 s53, s53, 0
	s_add_u32 s6, s73, s6
	s_addc_u32 s7, s74, s7
	s_add_u32 s6, s6, s55
	v_lshlrev_b32_e32 v0, 11, v204
	s_addc_u32 s7, s7, 0
	v_lshl_add_u64 v[2:3], s[52:53], 0, v[0:1]
	s_lshl_b32 s52, s62, 3
	s_ashr_i32 s53, s52, 31
	v_lshl_add_u64 v[196:197], s[52:53], 1, v[2:3]
	s_lshl_b32 s52, s62, 4
	v_lshrrev_b32_e32 v0, 2, v204
	v_and_or_b32 v0, s52, 48, v0
	v_lshlrev_b32_e32 v0, 11, v0
	v_lshl_add_u64 v[2:3], s[6:7], 0, v[0:1]
	s_ashr_i32 s6, s56, 3
	s_andn2_b32 s6, s6, 31
	s_ashr_i32 s7, s6, 31
	s_lshl_b32 s55, s62, 10
	v_lshlrev_b32_e32 v205, 3, v34
	s_cmp_lg_u32 0, -1
	v_lshl_add_u64 v[2:3], s[6:7], 1, v[2:3]
	v_and_b32_e32 v209, 24, v205
	s_cselect_b32 s6, 0, 0
	v_lshlrev_b32_e32 v0, 1, v209
	s_add_i32 s64, s55, s6
	s_mov_b32 s6, m0
	s_mov_b32 m0, s64
	s_nop 0
	global_load_lds_dwordx4 v[196:197], off
	s_mov_b32 m0, s6
	v_lshl_add_u64 v[198:199], v[2:3], 0, v[0:1]
	s_add_i32 s65, s64, 0x6000
	s_mov_b32 s6, m0
	s_mov_b32 m0, s65
	s_nop 0
	global_load_lds_dwordx4 v[198:199], off
	s_mov_b32 m0, s6
	s_sub_i32 s66, s60, s54
	v_lshl_add_u64 v[2:3], v[196:197], 0, s[40:41]
	s_add_i32 s6, s64, 0x2000
	s_mov_b32 s7, m0
	s_mov_b32 m0, s6
	s_nop 0
	global_load_lds_dwordx4 v[2:3], off
	s_mov_b32 m0, s7
	v_lshlrev_b32_e32 v2, 2, v34
	s_lshl_b32 s57, s66, 6
	s_nop 0
	v_cmp_gt_i32_e32 vcc, s57, v2
	s_and_saveexec_b64 s[6:7], vcc
	s_cbranch_execz .LBB0_357
	s_lshl_b32 s52, s54, 6
	s_add_i32 s59, s63, s59
	s_ashr_i32 s53, s52, 31
	s_add_i32 vcc_lo, s59, s61
	s_mov_b32 vcc_hi, s11
	s_lshl_b64 vcc, vcc, 14
	s_lshl_b64 s[52:53], s[52:53], 2
	s_add_u32 s52, s77, s52
	s_addc_u32 s53, s78, s53
	s_add_u32 s52, s52, vcc_lo
	v_ashrrev_i32_e32 v3, 31, v2
	s_addc_u32 s53, s53, vcc_hi
	v_lshl_add_u32 v0, v2, 2, s95
	v_lshl_add_u64 v[4:5], v[2:3], 2, s[52:53]
	s_mov_b64 s[52:53], 0
	global_load_dwordx4 v[6:9], v[4:5], off
	v_add_u32_e32 v2, 0x800, v2
	v_lshl_add_u64 v[4:5], v[4:5], 0, s[42:43]
	v_cmp_gt_i32_e32 vcc, s57, v2
	s_and_saveexec_b64 s[52:53], vcc
	s_cbranch_execz .Lkb_one
	global_load_dwordx4 v[226:229], v[4:5], off
	v_add_u32_e32 v2, 0x800, v2
	v_lshl_add_u64 v[4:5], v[4:5], 0, s[42:43]
.Lkb_one:
	s_mov_b64 exec, s[52:53]
	s_waitcnt vmcnt(0)
	ds_write_b128 v0, v[6:9]
	s_and_b64 exec, s[52:53], vcc
	s_cbranch_execz .LBB0_357
	ds_write_b128 v0, v[226:229] offset:8192
	v_add_u32_e32 v0, 0x4000, v0
	v_cmp_gt_i32_e32 vcc, s57, v2
	s_and_b64 exec, exec, vcc
	s_cbranch_execz .LBB0_357
	s_mov_b64 s[52:53], 0
